# attention hot loops: the lgkmcnt(0) waits left behind the permlane32 row-max merge removed (nothing outstanding there)
# baseline (speedup 1.0000x reference)
; #define LAS __attribute__((address_space(3)))
; DI float fexp2(float x) { return __builtin_amdgcn_exp2f(x); }
; #define ATT_LOAD(t) do { _Pragma("unroll") for (int j = 0; j < 3; ++j) { const int id = tid + 512 * j; const int ch = id % 24; kreg[j] = *(const u32x4*)(ksrc[j] + (size_t)(t) * (ch < 16 ? kstep_n : kstep_p)); } \
;         _Pragma("unroll") for (int j = 0; j < 2; ++j) vreg[j] = *(const u32x4*)(vsrc[j] + (size_t)(t) * 8192); } while (0)
; DI void attn_item(LAS unsigned char* lds, int bh, int qb, const bf16_t* QH, const bf16_t* KN, const bf16_t* KPE, const bf16_t* VT, const bf16_t* P, bf16_t* MIX) {
;     ...
;     for (int t = 0; t < ntile; ++t) {
;         __syncthreads();
;         if (t + 1 < ntile) { ATT_STORE((t + 1) & 1); if (t + 2 < ntile) ATT_LOAD(t + 2); }
;         LAS unsigned char* kb = lds + (t & 1) * ATT_STAGE; LAS unsigned char* vb = kb + KBUF_B;
;         f32x16 S;
; #pragma unroll
;         for (int i = 0; i < 16; ++i) S[i] = 0.f;
;         { const LAS unsigned char* kp = kb + (kh * 32 + r) * KROW + 16 * h2;
;           __builtin_amdgcn_s_setprio(1);
; #pragma unroll
;           for (int ks = 0; ks < 12; ++ks) { const bf16x8 a = *(const LAS bf16x8*)(kp + 32 * ks); S = __builtin_amdgcn_mfma_f32_32x32x16_bf16(a, Qf[ks], S, 0, 0, 0); }
;           __builtin_amdgcn_sched_group_barrier(0x100, 4, 0);
; #pragma unroll
;           for (int i = 0; i < 8; ++i) { __builtin_amdgcn_sched_group_barrier(0x008, 1, 0); __builtin_amdgcn_sched_group_barrier(0x100, 1, 0); }
;           __builtin_amdgcn_sched_group_barrier(0x008, 4, 0);
;           __builtin_amdgcn_s_setprio(0); }
;         const bool diag = (t >= 2 * qb);
;         if (diag) {
;             const int key0 = t * 64 + kh * 32 + 4 * h2;
; #pragma unroll
;             for (int i = 0; i < 16; ++i) { const int key = key0 + (i & 3) + 8 * (i >> 2); if (key > qpos) S[i] = NEG; }
;         }
;         float mx = S[0];
; #pragma unroll
;         for (int i = 1; i < 16; ++i) mx = fmaxf(mx, S[i]);
;         mx = fmaxf(mx, __shfl_xor(mx, 32));
;         if (__any(mx > mrow + 8.f)) {
;             const float mnew = fmaxf(mrow, mx);
;             const float alpha = fexp2(mrow - mnew);
;             mrow = mnew; lrow *= alpha;
; #pragma unroll
;             for (int d = 0; d < 4; ++d)
; #pragma unroll
;                 for (int i = 0; i < 16; ++i) O[d][i] *= alpha;
;         }
.LBB0_594:
	s_bitcmp1_b32 s22, 0
	s_cselect_b32 s40, 0, 0xb400
	s_cselect_b32 s44, 0xb400, 0
	s_add_i32 s40, s40, 0
	v_add_u32_e32 v64, s40, v171
	s_waitcnt lgkmcnt(0)
	s_barrier
	s_waitcnt vmcnt(4)
	ds_write_b128 v64, v[128:131]
	v_add_u32_e32 v64, s40, v173
	s_waitcnt vmcnt(3)
	ds_write_b128 v64, v[132:135]
	v_add_u32_e32 v64, s40, v220
	s_waitcnt vmcnt(0)
	ds_write_b128 v64, v[144:147]
	v_add_u32_e32 v64, s40, v221
	ds_write_b128 v64, v[136:139] offset:25600
	v_add_u32_e32 v64, s40, v222
	ds_write_b128 v64, v[140:143] offset:25600
	v_lshlrev_b64 v[64:65], v168, s[22:23]
	v_lshl_add_u64 v[64:65], v[64:65], 1, v[190:191]
	global_load_dwordx4 v[128:131], v[64:65], off
	v_lshlrev_b64 v[64:65], v170, s[22:23]
	v_lshl_add_u64 v[64:65], v[64:65], 1, v[192:193]
	global_load_dwordx4 v[132:135], v[64:65], off
	v_lshlrev_b64 v[64:65], v172, s[22:23]
	v_lshl_add_u64 v[64:65], v[64:65], 1, v[194:195]
	global_load_dwordx4 v[144:147], v[64:65], off
	global_load_dwordx4 v[136:139], v[218:219], off
	global_load_dwordx4 v[140:143], v[216:217], off
	s_add_i32 s44, s44, 0
	v_add3_u32 v235, s44, v233, v164
	s_setprio 1
	ds_read_b128 v[64:67], v235
	ds_read_b128 v[240:243], v235 offset:32
	ds_read_b128 v[244:247], v235 offset:64
	ds_read_b128 v[248:251], v235 offset:96
	s_waitcnt lgkmcnt(3)
	v_mfma_f32_32x32x16_bf16 v[64:79], v[64:67], v[124:127], 0
	ds_read_b128 v[236:239], v235 offset:128
	s_waitcnt lgkmcnt(3)
	v_mfma_f32_32x32x16_bf16 v[64:79], v[240:243], v[120:123], v[64:79]
	ds_read_b128 v[240:243], v235 offset:160
	s_waitcnt lgkmcnt(3)
	v_mfma_f32_32x32x16_bf16 v[64:79], v[244:247], v[116:119], v[64:79]
	ds_read_b128 v[244:247], v235 offset:192
	s_waitcnt lgkmcnt(3)
	v_mfma_f32_32x32x16_bf16 v[64:79], v[248:251], v[112:115], v[64:79]
	ds_read_b128 v[248:251], v235 offset:224
	s_waitcnt lgkmcnt(3)
	v_mfma_f32_32x32x16_bf16 v[64:79], v[236:239], v[108:111], v[64:79]
	ds_read_b128 v[236:239], v235 offset:256
	s_waitcnt lgkmcnt(3)
	v_mfma_f32_32x32x16_bf16 v[64:79], v[240:243], v[104:107], v[64:79]
	ds_read_b128 v[240:243], v235 offset:288
	s_waitcnt lgkmcnt(3)
	v_mfma_f32_32x32x16_bf16 v[64:79], v[244:247], v[100:103], v[64:79]
	ds_read_b128 v[244:247], v235 offset:320
	s_waitcnt lgkmcnt(3)
	v_mfma_f32_32x32x16_bf16 v[64:79], v[248:251], v[96:99], v[64:79]
	ds_read_b128 v[248:251], v235 offset:352
	s_waitcnt lgkmcnt(3)
	v_mfma_f32_32x32x16_bf16 v[64:79], v[236:239], v[84:87], v[64:79]
	s_waitcnt lgkmcnt(2)
	v_mfma_f32_32x32x16_bf16 v[64:79], v[240:243], v[88:91], v[64:79]
	s_waitcnt lgkmcnt(1)
	v_mfma_f32_32x32x16_bf16 v[64:79], v[244:247], v[92:95], v[64:79]
	s_waitcnt lgkmcnt(0)
	v_mfma_f32_32x32x16_bf16 v[64:79], v[248:251], v[80:83], v[64:79]
	s_setprio 0
	s_nop 10
	v_max_f32_e32 v235, v65, v65
	v_max_f32_e32 v236, v64, v64
	v_max_f32_e32 v235, v236, v235
	v_max3_f32 v235, v235, v66, v67
	v_max3_f32 v235, v235, v68, v69
	v_max3_f32 v235, v235, v70, v71
	v_max3_f32 v235, v235, v72, v73
	v_max3_f32 v235, v235, v74, v75
	v_max3_f32 v235, v235, v76, v77
	v_max3_f32 v235, v235, v78, v79
	v_mov_b32_e32 v236, v235
	s_nop 1
	v_permlane32_swap_b32_e32 v236, v235
	s_nop 0
	v_max_f32_e32 v236, v236, v236
	v_max_f32_e32 v235, v235, v236
	v_add_f32_e32 v236, 0x41000000, v214
	v_cmp_gt_f32_e32 vcc, v235, v236
	s_cbranch_vccz .LBB0_593
	v_max_f32_e32 v235, v235, v235
	v_max_f32_e32 v236, v214, v214
	v_max_f32_e32 v235, v236, v235
	v_sub_f32_e32 v214, v214, v235
	v_exp_f32_e32 v214, v214
	s_nop 0
	v_pk_mul_f32 v[62:63], v[62:63], v[214:215] op_sel_hi:[1,0]
	v_pk_mul_f32 v[60:61], v[60:61], v[214:215] op_sel_hi:[1,0]
	v_pk_mul_f32 v[58:59], v[58:59], v[214:215] op_sel_hi:[1,0]
	v_pk_mul_f32 v[56:57], v[56:57], v[214:215] op_sel_hi:[1,0]
	v_pk_mul_f32 v[54:55], v[54:55], v[214:215] op_sel_hi:[1,0]
	v_pk_mul_f32 v[52:53], v[52:53], v[214:215] op_sel_hi:[1,0]
	v_pk_mul_f32 v[50:51], v[50:51], v[214:215] op_sel_hi:[1,0]
	v_pk_mul_f32 v[48:49], v[48:49], v[214:215] op_sel_hi:[1,0]
	v_pk_mul_f32 v[46:47], v[46:47], v[214:215] op_sel_hi:[1,0]
	v_pk_mul_f32 v[44:45], v[44:45], v[214:215] op_sel_hi:[1,0]
	v_pk_mul_f32 v[42:43], v[42:43], v[214:215] op_sel_hi:[1,0]
	v_pk_mul_f32 v[40:41], v[40:41], v[214:215] op_sel_hi:[1,0]
	v_pk_mul_f32 v[38:39], v[38:39], v[214:215] op_sel_hi:[1,0]
	v_pk_mul_f32 v[36:37], v[36:37], v[214:215] op_sel_hi:[1,0]
	v_pk_mul_f32 v[34:35], v[34:35], v[214:215] op_sel_hi:[1,0]
	v_pk_mul_f32 v[32:33], v[32:33], v[214:215] op_sel_hi:[1,0]
	v_pk_mul_f32 v[30:31], v[30:31], v[214:215] op_sel_hi:[1,0]
	v_pk_mul_f32 v[28:29], v[28:29], v[214:215] op_sel_hi:[1,0]
	v_pk_mul_f32 v[26:27], v[26:27], v[214:215] op_sel_hi:[1,0]
	v_pk_mul_f32 v[24:25], v[24:25], v[214:215] op_sel_hi:[1,0]
	v_pk_mul_f32 v[22:23], v[22:23], v[214:215] op_sel_hi:[1,0]
	v_pk_mul_f32 v[20:21], v[20:21], v[214:215] op_sel_hi:[1,0]
	v_pk_mul_f32 v[18:19], v[18:19], v[214:215] op_sel_hi:[1,0]
	v_pk_mul_f32 v[16:17], v[16:17], v[214:215] op_sel_hi:[1,0]
	v_pk_mul_f32 v[14:15], v[14:15], v[214:215] op_sel_hi:[1,0]
	v_pk_mul_f32 v[12:13], v[12:13], v[214:215] op_sel_hi:[1,0]
	v_pk_mul_f32 v[10:11], v[10:11], v[214:215] op_sel_hi:[1,0]
	v_pk_mul_f32 v[8:9], v[8:9], v[214:215] op_sel_hi:[1,0]
	v_pk_mul_f32 v[6:7], v[6:7], v[214:215] op_sel_hi:[1,0]
	v_pk_mul_f32 v[4:5], v[4:5], v[214:215] op_sel_hi:[1,0]
	v_pk_mul_f32 v[2:3], v[2:3], v[214:215] op_sel_hi:[1,0]
	v_pk_mul_f32 v[0:1], v[0:1], v[214:215] op_sel_hi:[1,0]
	v_mul_f32_e32 v234, v234, v214
	v_mov_b32_e32 v214, v235
	s_branch .LBB0_593

; DI float fexp2(float x) { return __builtin_amdgcn_exp2f(x); }
; DI void attn_item(LAS unsigned char* lds, int bh, int qb, const bf16_t* QH, const bf16_t* KN, const bf16_t* KPE, const bf16_t* VT, const bf16_t* P, bf16_t* MIX) {
;     ...
;         float mx = S[0];
; #pragma unroll
;         for (int i = 1; i < 16; ++i) mx = fmaxf(mx, S[i]);
;         mx = fmaxf(mx, __shfl_xor(mx, 32));
;         if (__any(mx > mrow + 8.f)) {
;             const float mnew = fmaxf(mrow, mx);
;             const float alpha = fexp2(mrow - mnew);
;             mrow = mnew; lrow *= alpha;
; #pragma unroll
;             for (int d = 0; d < 4; ++d)
; #pragma unroll
;                 for (int i = 0; i < 16; ++i) O[d][i] *= alpha;
;         }
.LBB0_614:
	s_nop 6
	v_max_f32_e32 v185, v65, v65
	v_max_f32_e32 v187, v64, v64
	v_max_f32_e32 v185, v187, v185
	v_max3_f32 v185, v185, v66, v67
	v_max3_f32 v185, v185, v68, v69
	v_max3_f32 v185, v185, v70, v71
	v_max3_f32 v185, v185, v72, v73
	v_max3_f32 v185, v185, v74, v75
	v_max3_f32 v185, v185, v76, v77
	v_max3_f32 v185, v185, v78, v79
	v_mov_b32_e32 v187, v185
	s_nop 1
	v_permlane32_swap_b32_e32 v187, v185
	s_nop 0
	v_max_f32_e32 v187, v187, v187
	v_max_f32_e32 v185, v185, v187
	v_add_f32_e32 v187, 0x41000000, v200
	v_cmp_gt_f32_e32 vcc, v185, v187
	s_cbranch_vccz .Lsel609
	v_max_f32_e32 v185, v185, v185
	v_max_f32_e32 v187, v200, v200
	v_max_f32_e32 v185, v187, v185
	v_sub_f32_e32 v187, v200, v185
	v_exp_f32_e32 v200, v187
	s_nop 0
	v_pk_mul_f32 v[62:63], v[62:63], v[200:201] op_sel_hi:[1,0]
	v_pk_mul_f32 v[60:61], v[60:61], v[200:201] op_sel_hi:[1,0]
	v_pk_mul_f32 v[58:59], v[58:59], v[200:201] op_sel_hi:[1,0]
	v_pk_mul_f32 v[56:57], v[56:57], v[200:201] op_sel_hi:[1,0]
	v_pk_mul_f32 v[54:55], v[54:55], v[200:201] op_sel_hi:[1,0]
	v_pk_mul_f32 v[52:53], v[52:53], v[200:201] op_sel_hi:[1,0]
	v_pk_mul_f32 v[50:51], v[50:51], v[200:201] op_sel_hi:[1,0]
	v_pk_mul_f32 v[48:49], v[48:49], v[200:201] op_sel_hi:[1,0]
	v_pk_mul_f32 v[46:47], v[46:47], v[200:201] op_sel_hi:[1,0]
	v_pk_mul_f32 v[44:45], v[44:45], v[200:201] op_sel_hi:[1,0]
	v_pk_mul_f32 v[42:43], v[42:43], v[200:201] op_sel_hi:[1,0]
	v_pk_mul_f32 v[40:41], v[40:41], v[200:201] op_sel_hi:[1,0]
	v_pk_mul_f32 v[38:39], v[38:39], v[200:201] op_sel_hi:[1,0]
	v_pk_mul_f32 v[36:37], v[36:37], v[200:201] op_sel_hi:[1,0]
	v_pk_mul_f32 v[34:35], v[34:35], v[200:201] op_sel_hi:[1,0]
	v_pk_mul_f32 v[32:33], v[32:33], v[200:201] op_sel_hi:[1,0]
	v_pk_mul_f32 v[30:31], v[30:31], v[200:201] op_sel_hi:[1,0]
	v_pk_mul_f32 v[28:29], v[28:29], v[200:201] op_sel_hi:[1,0]
	v_pk_mul_f32 v[26:27], v[26:27], v[200:201] op_sel_hi:[1,0]
	v_pk_mul_f32 v[24:25], v[24:25], v[200:201] op_sel_hi:[1,0]
	v_pk_mul_f32 v[22:23], v[22:23], v[200:201] op_sel_hi:[1,0]
	v_pk_mul_f32 v[20:21], v[20:21], v[200:201] op_sel_hi:[1,0]
	v_pk_mul_f32 v[18:19], v[18:19], v[200:201] op_sel_hi:[1,0]
	v_pk_mul_f32 v[16:17], v[16:17], v[200:201] op_sel_hi:[1,0]
	v_pk_mul_f32 v[14:15], v[14:15], v[200:201] op_sel_hi:[1,0]
	v_pk_mul_f32 v[12:13], v[12:13], v[200:201] op_sel_hi:[1,0]
	v_pk_mul_f32 v[10:11], v[10:11], v[200:201] op_sel_hi:[1,0]
	v_pk_mul_f32 v[8:9], v[8:9], v[200:201] op_sel_hi:[1,0]
	v_pk_mul_f32 v[6:7], v[6:7], v[200:201] op_sel_hi:[1,0]
	v_pk_mul_f32 v[4:5], v[4:5], v[200:201] op_sel_hi:[1,0]
	v_pk_mul_f32 v[2:3], v[2:3], v[200:201] op_sel_hi:[1,0]
	v_pk_mul_f32 v[0:1], v[0:1], v[200:201] op_sel_hi:[1,0]
	v_mul_f32_e32 v183, v183, v200
	v_mov_b32_e32 v200, v185
	s_branch .Lsel609
